# DIFF combine preamble: lambda vectors and sub-LN weights loaded in one batch while the attention output stores drain (was three serial load-wait rounds)
# baseline (speedup 1.0000x reference)
.LBB0_708:
	v_mov_b32_e32 v16, v244
	v_and_b32_e32 v228, 63, v16
	v_lshlrev_b32_e32 v236, 3, v16
	v_lshlrev_b32_e32 v228, 2, v228
	v_and_b32_e32 v236, 0x78, v236
	v_readlane_b32 s100, v253, 0
	v_readlane_b32 s101, v253, 1
	v_or_b32_e32 v236, s64, v236
	v_mov_b32_e32 v237, 0
	global_load_dword v229, v228, s[8:9]
	global_load_dword v230, v228, s[8:9] offset:256
	global_load_dword v231, v228, s[8:9] offset:512
	global_load_dword v232, v228, s[8:9] offset:768
	v_lshl_add_u64 v[234:235], v[236:237], 2, s[100:101]
	global_load_dwordx4 v[212:215], v[234:235], off offset:16
	global_load_dwordx4 v[208:211], v[234:235], off
	s_waitcnt vmcnt(0) lgkmcnt(0)
	s_waitcnt vmcnt(0)
	v_mov_b32_e32 v5, v1
	v_and_b32_e32 v0, 63, v16
	v_lshlrev_b32_e32 v0, 2, v0
	s_nop 0
	s_nop 0
	v_readlane_b32 s52, v253, 0
	v_readlane_b32 s53, v253, 1
	s_mov_b64 s[48:49], s[52:53]
	s_lshl_b64 s[4:5], s[16:17], 11
	s_ashr_i32 s15, s14, 31
	v_readlane_b32 s7, v255, 5
	s_add_u32 s7, s7, s22
	v_readlane_b32 s54, v253, 2
	v_readlane_b32 s55, v253, 3
	v_readlane_b32 s56, v253, 4
	v_readlane_b32 s57, v253, 5
	v_readlane_b32 s58, v253, 6
	v_readlane_b32 s59, v253, 7
	s_mov_b64 s[52:53], s[56:57]
	s_mov_b64 s[54:55], s[58:59]
	s_mov_b32 s6, 8
	v_mov_b32_e32 v2, v229
	v_mov_b32_e32 v3, v230
	v_mul_f32_e32 v4, v2, v3
	s_nop 1
	v_mov_b32_dpp v5, v4 quad_perm:[1,0,3,2] row_mask:0xf bank_mask:0xf
	v_fmac_f32_e32 v5, v2, v3
	s_nop 1
	v_add_f32_dpp v2, v5, v5 quad_perm:[2,3,0,1] row_mask:0xf bank_mask:0xf bound_ctrl:1
	v_mov_b32_e32 v5, v1
	s_nop 0
	v_add_f32_dpp v2, v2, v2 row_half_mirror row_mask:0xf bank_mask:0xf bound_ctrl:1
	s_nop 1
	v_add_f32_dpp v2, v2, v2 row_mirror row_mask:0xf bank_mask:0xf bound_ctrl:1
	v_mov_b32_e32 v3, v2
	s_nop 1
	v_permlane16_swap_b32_e32 v2, v3
	v_add_f32_e32 v2, v2, v3
	v_mov_b32_e32 v3, v2
	s_nop 1
	v_permlane32_swap_b32_e32 v2, v3
	v_add_f32_e32 v2, v2, v3
	v_mov_b32_e32 v3, v231
	s_nop 0
	v_mov_b32_e32 v0, v232
	v_mul_f32_e32 v2, 0x3fb8aa3b, v2
	v_exp_f32_e32 v2, v2
	s_nop 0
	v_mul_f32_e32 v4, v3, v0
	s_nop 1
	v_mov_b32_dpp v5, v4 quad_perm:[1,0,3,2] row_mask:0xf bank_mask:0xf
	v_fmac_f32_e32 v5, v3, v0
	s_nop 1
	v_add_f32_dpp v0, v5, v5 quad_perm:[2,3,0,1] row_mask:0xf bank_mask:0xf bound_ctrl:1
	s_nop 1
	v_add_f32_dpp v0, v0, v0 row_half_mirror row_mask:0xf bank_mask:0xf bound_ctrl:1
	s_nop 1
	v_add_f32_dpp v0, v0, v0 row_mirror row_mask:0xf bank_mask:0xf bound_ctrl:1
	v_mov_b32_e32 v3, v0
	s_nop 1
	v_permlane16_swap_b32_e32 v0, v3
	v_add_f32_e32 v0, v0, v3
	v_mov_b32_e32 v3, v0
	s_nop 1
	v_permlane32_swap_b32_e32 v0, v3
	v_add_f32_e32 v0, v0, v3
	v_mul_f32_e32 v0, 0x3fb8aa3b, v0
	v_exp_f32_e32 v0, v0
	s_nop 0
	v_sub_f32_e32 v0, v2, v0
	v_add_f32_e32 v6, v152, v0
	v_lshlrev_b32_e32 v0, 3, v16
	v_and_b32_e32 v0, 0x78, v0
	v_or_b32_e32 v0, s64, v0
	v_lshl_add_u64 v[8:9], v[0:1], 2, s[48:49]
	v_mov_b32_e32 v2, v212
	v_mov_b32_e32 v3, v213
	v_mov_b32_e32 v4, v214
	v_mov_b32_e32 v5, v215
	s_nop 0
	v_mov_b32_e32 v8, v208
	v_mov_b32_e32 v9, v209
	v_mov_b32_e32 v10, v210
	v_mov_b32_e32 v11, v211
	v_ashrrev_i32_e32 v0, 1, v16
	v_mov_b32_e32 v7, v6
	s_nop 0
	v_pk_mul_f32 v[12:13], v[130:131], v[2:3]
	v_bfe_u32 v2, v16, 4, 2
	v_mov_b32_e32 v3, v1
	v_pk_mul_f32 v[14:15], v[130:131], v[4:5]
	v_and_b32_e32 v4, 0xffffffe0, v0
	v_lshl_add_u64 v[2:3], v[2:3], 0, s[14:15]
	v_readlane_b32 s14, v255, 6
	v_ashrrev_i32_e32 v5, 31, v4
	s_addc_u32 s14, s14, 0
	v_lshl_add_u64 v[2:3], v[2:3], 0, v[4:5]
	s_add_u32 s10, s7, s10
	v_lshlrev_b64 v[4:5], 13, v[2:3]
	s_addc_u32 s11, s14, s11
	s_lshl_b32 s7, s23, 9
	v_and_b32_e32 v0, 15, v16
	v_lshl_add_u64 v[16:17], s[10:11], 0, v[4:5]
	s_add_u32 s10, s54, s7
	v_lshlrev_b64 v[4:5], 11, v[2:3]
	s_addc_u32 s11, s55, 0
	v_readlane_b32 s7, v255, 7
	v_lshl_add_u64 v[4:5], s[12:13], 0, v[4:5]
	s_add_u32 s12, s7, s22
	v_readlane_b32 s7, v255, 8
	s_addc_u32 s13, s7, 0
	v_lshl_add_u64 v[2:3], v[2:3], 0, s[4:5]
	v_readlane_b32 s4, v255, 9
	s_add_u32 s4, s4, s22
	v_readlane_b32 s5, v255, 10
	v_lshl_add_u64 v[18:19], s[10:11], 0, v[4:5]
	v_lshl_add_u64 v[20:21], s[12:13], 0, v[4:5]
	v_lshlrev_b64 v[4:5], 13, v[2:3]
	s_addc_u32 s5, s5, 0
	v_lshl_add_u64 v[22:23], s[4:5], 0, v[4:5]
	s_add_u32 s4, s80, s22
	v_lshlrev_b64 v[2:3], 11, v[2:3]
	s_addc_u32 s5, s83, 0
	s_nop 0
	v_pk_mul_f32 v[8:9], v[130:131], v[8:9]
	v_pk_mul_f32 v[10:11], v[130:131], v[10:11]
	v_lshlrev_b32_e32 v0, 4, v0
	v_lshl_add_u64 v[24:25], s[10:11], 0, v[2:3]
	v_lshl_add_u64 v[26:27], s[4:5], 0, v[2:3]
